# v67 + stream compute block: K fragment LDS reads up front into spare staging VGPRs, transposed V reads issued before the softmax arithmetic
# baseline (speedup 1.0000x reference)
.LBB0_543:
	ds_read_b128 v[38:41], v229
	ds_read_b128 v[42:45], v230
	ds_read_b128 v[46:49], v231
	ds_read_b128 v[50:53], v232
	ds_read_b128 v[54:57], v229 offset:4096
	ds_read_b128 v[58:61], v230 offset:4096
	ds_read_b128 v[62:65], v231 offset:4096
	ds_read_b128 v[66:69], v232 offset:4096
	s_nop 0
	s_nop 0
	s_add_i32 s22, s22, 32
	s_cmp_eq_u32 s25, 16
	s_nop 0
	s_waitcnt lgkmcnt(7)
	v_mfma_f32_16x16x32_bf16 v[242:245], v[38:41], v[2:5], 0
	s_nop 0
	s_nop 0
	s_waitcnt lgkmcnt(6)
	v_mfma_f32_16x16x32_bf16 v[242:245], v[42:45], v[10:13], v[242:245]
	s_nop 0
	s_nop 0
	s_waitcnt lgkmcnt(5)
	v_mfma_f32_16x16x32_bf16 v[242:245], v[46:49], v[6:9], v[242:245]
	s_nop 0
	s_nop 0
	s_waitcnt lgkmcnt(4)
	v_mfma_f32_16x16x32_bf16 v[242:245], v[50:53], v[14:17], v[242:245]
	s_nop 0
	s_nop 6
	v_max_f32_e32 v179, v243, v243
	v_max_f32_e32 v180, v242, v242
	v_max_f32_e32 v179, v180, v179
	s_nop 0
	s_waitcnt lgkmcnt(3)
	v_mfma_f32_16x16x32_bf16 v[246:249], v[54:57], v[2:5], 0
	v_max_f32_e32 v180, v245, v245
	v_max_f32_e32 v181, v244, v244
	v_max_f32_e32 v180, v181, v180
	s_waitcnt lgkmcnt(2)
	v_mfma_f32_16x16x32_bf16 v[246:249], v[58:61], v[10:13], v[246:249]
	s_nop 0
	s_nop 0
	s_waitcnt lgkmcnt(1)
	v_mfma_f32_16x16x32_bf16 v[246:249], v[62:65], v[6:9], v[246:249]
	s_nop 0
	s_nop 0
	s_waitcnt lgkmcnt(0)
	v_mfma_f32_16x16x32_bf16 v[246:249], v[66:69], v[14:17], v[246:249]
	ds_read_b64_tr_b16 v[70:71], v233 offset:8192
	ds_read_b64_tr_b16 v[72:73], v233 offset:12288
	ds_read_b64_tr_b16 v[74:75], v234 offset:8192
	ds_read_b64_tr_b16 v[76:77], v234 offset:12288
	ds_read_b64_tr_b16 v[78:79], v235 offset:8192
	ds_read_b64_tr_b16 v[80:81], v235 offset:12288
	ds_read_b64_tr_b16 v[82:83], v236 offset:8192
	ds_read_b64_tr_b16 v[84:85], v236 offset:12288
	ds_read_b64_tr_b16 v[86:87], v237 offset:8192
	ds_read_b64_tr_b16 v[88:89], v237 offset:12288
	ds_read_b64_tr_b16 v[90:91], v238 offset:8192
	ds_read_b64_tr_b16 v[92:93], v238 offset:12288
	ds_read_b64_tr_b16 v[138:139], v239 offset:8192
	ds_read_b64_tr_b16 v[140:141], v239 offset:12288
	ds_read_b64_tr_b16 v[142:143], v240 offset:8192
	ds_read_b64_tr_b16 v[144:145], v240 offset:12288
	s_nop 7
	v_max_f32_e32 v181, v249, v249
	v_max_f32_e32 v186, v248, v248
	v_max_f32_e32 v181, v186, v181
	v_max3_f32 v181, v246, v247, v181
	v_max3_f32 v179, v179, v180, v181
	v_mov_b32_e32 v180, v179
	s_nop 1
	v_permlane16_swap_b32_e32 v179, v180
	v_max_f32_e32 v180, v180, v180
	v_max_f32_e32 v179, v179, v179
	v_max_f32_e32 v179, v179, v180
	v_mov_b32_e32 v180, v179
	s_nop 1
	v_permlane32_swap_b32_e32 v179, v180
	v_max3_f32 v241, v178, v179, v180
	v_sub_f32_e32 v178, v178, v241
	v_exp_f32_e32 v186, v178
	v_sub_f32_e32 v181, v245, v241
	v_sub_f32_e32 v180, v244, v241
	v_sub_f32_e32 v179, v243, v241
	v_sub_f32_e32 v178, v242, v241
	v_sub_f32_e32 v242, v249, v241
	v_sub_f32_e32 v243, v248, v241
	v_sub_f32_e32 v245, v247, v241
	v_sub_f32_e32 v244, v246, v241
	v_exp_f32_e32 v178, v178
	v_exp_f32_e32 v179, v179
	v_exp_f32_e32 v180, v180
	v_exp_f32_e32 v181, v181
	v_exp_f32_e32 v244, v244
	v_exp_f32_e32 v245, v245
	v_exp_f32_e32 v246, v243
	v_exp_f32_e32 v247, v242
	v_pk_mul_f32 v[136:137], v[136:137], v[186:187] op_sel_hi:[1,0]
	v_pk_add_f32 v[248:249], v[178:179], v[244:245]
	v_cvt_pk_bf16_f32 v178, v178, v179
	v_pk_add_f32 v[242:243], v[180:181], v[246:247]
	v_cvt_pk_bf16_f32 v179, v180, v181
	v_cvt_pk_bf16_f32 v180, v244, v245
	v_cvt_pk_bf16_f32 v181, v246, v247
	s_nop 0
	s_nop 0
	v_pk_mul_f32 v[134:135], v[134:135], v[186:187] op_sel_hi:[1,0]
	v_pk_mul_f32 v[132:133], v[132:133], v[186:187] op_sel_hi:[1,0]
	v_pk_mul_f32 v[130:131], v[130:131], v[186:187] op_sel_hi:[1,0]
	s_nop 0
	s_waitcnt lgkmcnt(14)
	v_mfma_f32_16x16x32_bf16 v[134:137], v[70:73], v[178:181], v[134:137]
	s_nop 0
	s_nop 0
	v_pk_mul_f32 v[128:129], v[128:129], v[186:187] op_sel_hi:[1,0]
	v_pk_mul_f32 v[126:127], v[126:127], v[186:187] op_sel_hi:[1,0]
	s_nop 0
	s_waitcnt lgkmcnt(12)
	v_mfma_f32_16x16x32_bf16 v[130:133], v[74:77], v[178:181], v[130:133]
	s_nop 0
	s_nop 0
	v_pk_mul_f32 v[124:125], v[124:125], v[186:187] op_sel_hi:[1,0]
	v_pk_mul_f32 v[122:123], v[122:123], v[186:187] op_sel_hi:[1,0]
	s_nop 0
	s_waitcnt lgkmcnt(10)
	v_mfma_f32_16x16x32_bf16 v[126:129], v[78:81], v[178:181], v[126:129]
	s_nop 0
	s_nop 0
	v_pk_mul_f32 v[116:117], v[116:117], v[186:187] op_sel_hi:[1,0]
	v_pk_mul_f32 v[114:115], v[114:115], v[186:187] op_sel_hi:[1,0]
	s_nop 0
	s_waitcnt lgkmcnt(8)
	v_mfma_f32_16x16x32_bf16 v[122:125], v[82:85], v[178:181], v[122:125]
	s_nop 0
	s_nop 0
	v_pk_mul_f32 v[104:105], v[104:105], v[186:187] op_sel_hi:[1,0]
	v_pk_mul_f32 v[102:103], v[102:103], v[186:187] op_sel_hi:[1,0]
	s_nop 0
	s_waitcnt lgkmcnt(6)
	v_mfma_f32_16x16x32_bf16 v[114:117], v[86:89], v[178:181], v[114:117]
	s_nop 0
	s_nop 0
	v_pk_mul_f32 v[100:101], v[100:101], v[186:187] op_sel_hi:[1,0]
	v_pk_mul_f32 v[98:99], v[98:99], v[186:187] op_sel_hi:[1,0]
	s_nop 0
	s_waitcnt lgkmcnt(4)
	v_mfma_f32_16x16x32_bf16 v[102:105], v[90:93], v[178:181], v[102:105]
	s_nop 0
	s_nop 0
	v_pk_mul_f32 v[96:97], v[96:97], v[186:187] op_sel_hi:[1,0]
	v_pk_mul_f32 v[94:95], v[94:95], v[186:187] op_sel_hi:[1,0]
	s_nop 0
	s_waitcnt lgkmcnt(2)
	v_mfma_f32_16x16x32_bf16 v[98:101], v[138:141], v[178:181], v[98:101]
	s_nop 0
	s_nop 0
	v_pk_mov_b32 v[250:251], v[248:249], v[242:243] op_sel:[1,0]
	v_mov_b32_e32 v249, v243
	s_nop 0
	s_waitcnt lgkmcnt(0)
	v_mfma_f32_16x16x32_bf16 v[94:97], v[142:145], v[178:181], v[94:97]
	v_add_f32_e64 v242, v250, v248
	v_add_f32_e64 v243, v251, v249
	v_add_f32_e32 v242, v242, v243
	v_fmac_f32_e32 v242, v193, v186
	s_cbranch_scc1 .LBB0_545
	v_mov_b32_e32 v193, v242
	v_mov_b32_e32 v178, v241
	s_mov_b32 s24, s25
	s_branch .LBB0_539

.LBB0_600:
	ds_read_b128 v[38:41], v221
	ds_read_b128 v[42:45], v227
	ds_read_b128 v[46:49], v228
	ds_read_b128 v[50:53], v229
	ds_read_b128 v[54:57], v221 offset:4096
	ds_read_b128 v[58:61], v227 offset:4096
	ds_read_b128 v[62:65], v228 offset:4096
	ds_read_b128 v[66:69], v229 offset:4096
	s_nop 0
	s_nop 0
	s_add_i32 s22, s22, 32
	s_cmp_eq_u32 s25, 16
	s_nop 0
	s_waitcnt lgkmcnt(7)
	v_mfma_f32_16x16x32_bf16 v[238:241], v[38:41], v[2:5], 0
	s_nop 0
	s_nop 0
	s_waitcnt lgkmcnt(6)
	v_mfma_f32_16x16x32_bf16 v[238:241], v[42:45], v[10:13], v[238:241]
	s_nop 0
	s_nop 0
	s_waitcnt lgkmcnt(5)
	v_mfma_f32_16x16x32_bf16 v[238:241], v[46:49], v[6:9], v[238:241]
	s_nop 0
	s_nop 0
	s_waitcnt lgkmcnt(4)
	v_mfma_f32_16x16x32_bf16 v[240:243], v[50:53], v[14:17], v[238:241]
	s_nop 0
	s_nop 6
	v_max_f32_e32 v179, v241, v241
	v_max_f32_e32 v180, v240, v240
	v_max_f32_e32 v179, v180, v179
	s_nop 0
	s_waitcnt lgkmcnt(3)
	v_mfma_f32_16x16x32_bf16 v[244:247], v[54:57], v[2:5], 0
	v_max_f32_e32 v180, v243, v243
	v_max_f32_e32 v181, v242, v242
	v_max_f32_e32 v180, v181, v180
	s_waitcnt lgkmcnt(2)
	v_mfma_f32_16x16x32_bf16 v[244:247], v[58:61], v[10:13], v[244:247]
	s_nop 0
	s_nop 0
	s_waitcnt lgkmcnt(1)
	v_mfma_f32_16x16x32_bf16 v[244:247], v[62:65], v[6:9], v[244:247]
	s_nop 0
	s_nop 0
	s_waitcnt lgkmcnt(0)
	v_mfma_f32_16x16x32_bf16 v[244:247], v[66:69], v[14:17], v[244:247]
	ds_read_b64_tr_b16 v[70:71], v230 offset:8192
	ds_read_b64_tr_b16 v[72:73], v230 offset:12288
	ds_read_b64_tr_b16 v[74:75], v231 offset:8192
	ds_read_b64_tr_b16 v[76:77], v231 offset:12288
	ds_read_b64_tr_b16 v[78:79], v232 offset:8192
	ds_read_b64_tr_b16 v[80:81], v232 offset:12288
	ds_read_b64_tr_b16 v[82:83], v233 offset:8192
	ds_read_b64_tr_b16 v[84:85], v233 offset:12288
	ds_read_b64_tr_b16 v[86:87], v234 offset:8192
	ds_read_b64_tr_b16 v[88:89], v234 offset:12288
	ds_read_b64_tr_b16 v[90:91], v235 offset:8192
	ds_read_b64_tr_b16 v[92:93], v235 offset:12288
	ds_read_b64_tr_b16 v[138:139], v236 offset:8192
	ds_read_b64_tr_b16 v[140:141], v236 offset:12288
	ds_read_b64_tr_b16 v[142:143], v237 offset:8192
	ds_read_b64_tr_b16 v[144:145], v237 offset:12288
	s_nop 7
	v_max_f32_e32 v181, v247, v247
	v_max_f32_e32 v186, v246, v246
	v_max_f32_e32 v181, v186, v181
	v_max3_f32 v181, v244, v245, v181
	v_max3_f32 v179, v179, v180, v181
	v_mov_b32_e32 v180, v179
	s_nop 1
	v_permlane16_swap_b32_e32 v179, v180
	v_max_f32_e32 v180, v180, v180
	v_max_f32_e32 v179, v179, v179
	v_max_f32_e32 v179, v179, v180
	v_mov_b32_e32 v180, v179
	s_nop 1
	v_permlane32_swap_b32_e32 v179, v180
	v_max3_f32 v238, v178, v179, v180
	v_sub_f32_e32 v178, v178, v238
	v_exp_f32_e32 v186, v178
	v_sub_f32_e32 v181, v243, v238
	v_sub_f32_e32 v180, v242, v238
	v_sub_f32_e32 v179, v241, v238
	v_sub_f32_e32 v178, v240, v238
	v_sub_f32_e32 v239, v247, v238
	v_sub_f32_e32 v242, v246, v238
	v_sub_f32_e32 v241, v245, v238
	v_sub_f32_e32 v240, v244, v238
	v_exp_f32_e32 v178, v178
	v_exp_f32_e32 v179, v179
	v_exp_f32_e32 v180, v180
	v_exp_f32_e32 v181, v181
	v_exp_f32_e32 v240, v240
	v_exp_f32_e32 v241, v241
	v_exp_f32_e32 v242, v242
	v_exp_f32_e32 v243, v239
	v_pk_mul_f32 v[136:137], v[136:137], v[186:187] op_sel_hi:[1,0]
	v_pk_add_f32 v[246:247], v[178:179], v[240:241]
	v_cvt_pk_bf16_f32 v178, v178, v179
	v_pk_add_f32 v[244:245], v[180:181], v[242:243]
	v_cvt_pk_bf16_f32 v179, v180, v181
	v_cvt_pk_bf16_f32 v180, v240, v241
	v_cvt_pk_bf16_f32 v181, v242, v243
	s_nop 0
	s_nop 0
	v_pk_mul_f32 v[134:135], v[134:135], v[186:187] op_sel_hi:[1,0]
	v_pk_mul_f32 v[132:133], v[132:133], v[186:187] op_sel_hi:[1,0]
	v_pk_mul_f32 v[130:131], v[130:131], v[186:187] op_sel_hi:[1,0]
	s_nop 0
	s_waitcnt lgkmcnt(14)
	v_mfma_f32_16x16x32_bf16 v[134:137], v[70:73], v[178:181], v[134:137]
	s_nop 0
	s_nop 0
	v_pk_mul_f32 v[128:129], v[128:129], v[186:187] op_sel_hi:[1,0]
	v_pk_mul_f32 v[126:127], v[126:127], v[186:187] op_sel_hi:[1,0]
	s_nop 0
	s_waitcnt lgkmcnt(12)
	v_mfma_f32_16x16x32_bf16 v[130:133], v[74:77], v[178:181], v[130:133]
	s_nop 0
	s_nop 0
	v_pk_mul_f32 v[124:125], v[124:125], v[186:187] op_sel_hi:[1,0]
	v_pk_mul_f32 v[122:123], v[122:123], v[186:187] op_sel_hi:[1,0]
	s_nop 0
	s_waitcnt lgkmcnt(10)
	v_mfma_f32_16x16x32_bf16 v[126:129], v[78:81], v[178:181], v[126:129]
	s_nop 0
	s_nop 0
	v_pk_mul_f32 v[116:117], v[116:117], v[186:187] op_sel_hi:[1,0]
	v_pk_mul_f32 v[114:115], v[114:115], v[186:187] op_sel_hi:[1,0]
	s_nop 0
	s_waitcnt lgkmcnt(8)
	v_mfma_f32_16x16x32_bf16 v[122:125], v[82:85], v[178:181], v[122:125]
	s_nop 0
	s_nop 0
	v_pk_mul_f32 v[104:105], v[104:105], v[186:187] op_sel_hi:[1,0]
	v_pk_mul_f32 v[102:103], v[102:103], v[186:187] op_sel_hi:[1,0]
	s_nop 0
	s_waitcnt lgkmcnt(6)
	v_mfma_f32_16x16x32_bf16 v[114:117], v[86:89], v[178:181], v[114:117]
	s_nop 0
	s_nop 0
	v_pk_mul_f32 v[100:101], v[100:101], v[186:187] op_sel_hi:[1,0]
	v_pk_mul_f32 v[98:99], v[98:99], v[186:187] op_sel_hi:[1,0]
	s_nop 0
	s_waitcnt lgkmcnt(4)
	v_mfma_f32_16x16x32_bf16 v[102:105], v[90:93], v[178:181], v[102:105]
	s_nop 0
	s_nop 0
	v_pk_mul_f32 v[96:97], v[96:97], v[186:187] op_sel_hi:[1,0]
	v_pk_mul_f32 v[94:95], v[94:95], v[186:187] op_sel_hi:[1,0]
	s_nop 0
	s_waitcnt lgkmcnt(2)
	v_mfma_f32_16x16x32_bf16 v[98:101], v[138:141], v[178:181], v[98:101]
	s_nop 0
	s_nop 0
	v_pk_mov_b32 v[248:249], v[246:247], v[244:245] op_sel:[1,0]
	v_mov_b32_e32 v247, v245
	s_nop 0
	s_waitcnt lgkmcnt(0)
	v_mfma_f32_16x16x32_bf16 v[94:97], v[142:145], v[178:181], v[94:97]
	v_add_f32_e64 v244, v248, v246
	v_add_f32_e64 v245, v249, v247
	v_add_f32_e32 v239, v244, v245
	v_fmac_f32_e32 v239, v189, v186
	s_cbranch_scc1 .LBB0_602
	v_mov_b32_e32 v189, v239
	v_mov_b32_e32 v178, v238
	s_mov_b32 s24, s25
	s_branch .LBB0_596
